# stick-breaking loop: m0 save/restore moves around the per-tile LDS-DMA issues removed
# speedup vs baseline: 1.0037x; 1.0009x over previous
; #define LAS __attribute__((address_space(3)))
; #define ATT_WAIT_BAR_N(N) asm volatile("s_waitcnt vmcnt(" #N ") lgkmcnt(0)\n\ts_barrier" ::: "memory")
; #define ATT_DMA(jt, slot) do { glds16(ksrc + (size_t)(jt) * 64 * D, (unsigned)__builtin_amdgcn_readfirstlane(lds0 + A_K + (slot) * 8192 + wid * 1024)); \
;                                glds16(vsrc + (size_t)(jt) * 64 * D, (unsigned)__builtin_amdgcn_readfirstlane(lds0 + A_V + (slot) * 8192 + wid * 1024)); } while (0)
; #define ATT_DMA(jt) do { const int s_ = (jt) & 7; glds16(ksrc + (size_t)(jt) * 64 * D, (unsigned)__builtin_amdgcn_readfirstlane(lds0 + B_K + s_ * 8192 + wid * 1024)); \
;                          glds16(vsrc + (size_t)(jt) * 64 * D, (unsigned)__builtin_amdgcn_readfirstlane(lds0 + B_V + s_ * 8192 + wid * 1024)); } while (0)
; __device__ __forceinline__ void prompt_unit_sb(const Args& a, int l, int b, int h, int qb, LAS unsigned char* lds) {
;     ...
;     for (int it = 0; ; ++it) {
;         const int need = jb - it;
;         if (need >= 3) ATT_WAIT_BAR_N(6); else if (need == 2) ATT_WAIT_BAR_N(4); else if (need == 1) ATT_WAIT_BAR_N(2); else ATT_WAIT_BAR_N(0);
;         if (it > 0) {
;             const u32x4 f0 = *(const LAS u32x4*)(flags + ((it - 1) & 1) * 8), f1 = *(const LAS u32x4*)(flags + ((it - 1) & 1) * 8 + 4);
;             if ((f0.x & f0.y & f0.z & f0.w & f1.x & f1.y & f1.z & f1.w) != 0u) break;
;         }
;         if (need >= 4) ATT_DMA(need - 4);
.LBB0_283:
	s_andn2_b64 vcc, exec, s[80:81]
	s_mov_b64 s[80:81], 0
	s_cbranch_vccnz .LBB0_269
	s_cmp_lt_i32 s89, 4
	s_cbranch_scc1 .LBB0_286
	s_add_i32 s80, s89, -4
	s_mov_b32 s81, s87
	s_lshl_b64 s[80:81], s[80:81], 17
	s_and_b32 s89, s94, 0xe000
	v_lshl_add_u64 v[2:3], v[162:163], 0, s[80:81]
	s_add_i32 s90, s89, s83
	s_mov_b32 m0, s90
	s_nop 0
	global_load_lds_dwordx4 v[2:3], off
	v_lshl_add_u64 v[2:3], v[164:165], 0, s[80:81]
	s_add_i32 s80, s89, s84
	s_mov_b32 m0, s80
	s_nop 0
	global_load_lds_dwordx4 v[2:3], off

; #define LAS __attribute__((address_space(3)))
; #define ATT_WAIT_BAR_N(N) asm volatile("s_waitcnt vmcnt(" #N ") lgkmcnt(0)\n\ts_barrier" ::: "memory")
; #define ATT_DMA(jt, slot) do { glds16(ksrc + (size_t)(jt) * 64 * D, (unsigned)__builtin_amdgcn_readfirstlane(lds0 + A_K + (slot) * 8192 + wid * 1024)); \
;                                glds16(vsrc + (size_t)(jt) * 64 * D, (unsigned)__builtin_amdgcn_readfirstlane(lds0 + A_V + (slot) * 8192 + wid * 1024)); } while (0)
; #define ATT_DMA(jt) do { const int s_ = (jt) & 7; glds16(ksrc + (size_t)(jt) * 64 * D, (unsigned)__builtin_amdgcn_readfirstlane(lds0 + B_K + s_ * 8192 + wid * 1024)); \
;                          glds16(vsrc + (size_t)(jt) * 64 * D, (unsigned)__builtin_amdgcn_readfirstlane(lds0 + B_V + s_ * 8192 + wid * 1024)); } while (0)
; __device__ __forceinline__ void prompt_unit_sb(const Args& a, int l, int b, int h, int qb, LAS unsigned char* lds) {
;     ...
;     for (int it = 0; ; ++it) {
;         const int need = jb - it;
;         if (need >= 3) ATT_WAIT_BAR_N(6); else if (need == 2) ATT_WAIT_BAR_N(4); else if (need == 1) ATT_WAIT_BAR_N(2); else ATT_WAIT_BAR_N(0);
;         if (it > 0) {
;             const u32x4 f0 = *(const LAS u32x4*)(flags + ((it - 1) & 1) * 8), f1 = *(const LAS u32x4*)(flags + ((it - 1) & 1) * 8 + 4);
;             if ((f0.x & f0.y & f0.z & f0.w & f1.x & f1.y & f1.z & f1.w) != 0u) break;
;         }
;         if (need >= 4) ATT_DMA(need - 4);
.LBB0_944:
	s_andn2_b64 vcc, exec, s[80:81]
	s_mov_b64 s[80:81], 0
	s_cbranch_vccnz .LBB0_930
	s_cmp_lt_i32 s89, 4
	s_cbranch_scc1 .LBB0_947
	s_add_i32 s76, s89, -4
	s_mov_b32 s77, s87
	s_lshl_b64 s[76:77], s[76:77], 17
	s_and_b32 s80, s96, 0xe000
	v_lshl_add_u64 v[2:3], v[164:165], 0, s[76:77]
	s_add_i32 s81, s80, s85
	s_mov_b32 m0, s81
	s_nop 0
	global_load_lds_dwordx4 v[2:3], off
	v_lshl_add_u64 v[2:3], v[166:167], 0, s[76:77]
	s_add_i32 s76, s80, s94
	s_mov_b32 m0, s76
	s_nop 0
	global_load_lds_dwordx4 v[2:3], off
